# attention item setup: all 27 rows of the per-wave bias table built with 3 LDS round trips (idle K fragment registers as staging) instead of 9 serial batches
# speedup vs baseline: 1.0089x; 1.0089x over previous
; #define TIDX get_tid_()
; DI float bf2f(bf16_t b) { return __uint_as_float(((unsigned)b) << 16); }
; DI int crow(int i, int h) { return (i & 3) + 8 * (i >> 2) + 4 * h; }
; DI void nsa_main_item(const Params& p, int b, int head, int qb, const unsigned char* blut, const float* tbl) {
;   const int lane = TIDX & 63, r = lane & 31, h = lane >> 5;
;   const int g = head / 3, bg = b * 2 + g;
;   const int t = qb * 32 + r;
;   const float* tblh = tbl + head * 32;
;   bf16x8 qf[4];
;   load_q(qf, (const bf16_t*)(p.ws + OFF_QN) + (size_t)(b * 4096 + t) * 384 + head * 64 + 8 * h);
;   const unsigned long long selm = ((const unsigned long long*)(p.ws + OFF_SELM))[(size_t)bg * 4096 + t];
;   const float* gates = (const float*)(p.ws + OFF_GATES) + (size_t)(b * 4096 + t) * 18 + head * 3;
;   const float g1 = gates[1];
;   f32x16 y0, y1;
;   {
;     const bf16_t* oc = (const bf16_t*)(p.ws + OFF_OC) + (size_t)(b * 4096 + t) * 384 + head * 64;
;     const bf16_t* yw = (const bf16_t*)(p.ws + OFF_Y) + (size_t)(b * 4096 + t) * 768 + head * 64;
; #pragma unroll
;     for (int i = 0; i < 16; ++i) { y0[i] = bf2f(oc[crow(i, h)]) + bf2f(yw[crow(i, h)]); y1[i] = bf2f(oc[32 + crow(i, h)]) + bf2f(yw[32 + crow(i, h)]); }
;   }
;   {
;     const bf16_t* K = (const bf16_t*)(p.ws + OFF_KSEL) + (size_t)bg * 4096 * 64;
;     const bf16_t* Vt = (const bf16_t*)(p.ws + OFF_VSELT) + (size_t)bg * 64 * 4096;
;     AttnSt st; attn_init(st);
;     attn_loop(st, qf, 0, qb, 32,
;     ...
;   for (;;) {
;     const int item = wave_fetch(ctr);
;     if (item >= 128 * 48) break;
;     const int qb = 127 - item / 48, sub = item % 48;
;     nsa_main_item(p, sub / 6, sub % 6, qb, blut, tbl);
.LfY_skip:
	s_or_b64 exec, exec, s[8:9]
	s_barrier
	ds_read_b32 v0, v0
	v_lshrrev_b32_e32 v1, 6, v129
	s_waitcnt lgkmcnt(0)
	v_add_u32_e32 v0, v0, v1
	s_movk_i32 s8, 0x300
	s_waitcnt lgkmcnt(0)
	v_cmp_gt_i32_e32 vcc, s8, v0
	s_mov_b64 s[8:9], -1
	s_and_saveexec_b64 s[14:15], vcc
	s_cbranch_execz .LBB0_702
	v_lshrrev_b32_e32 v1, 4, v0
	v_lshlrev_b32_e32 v1, 3, v1
	v_and_b32_e32 v2, 7, v0
	v_add_u32_e32 v1, v1, v2
	v_bfe_u32 v2, v0, 3, 1
	v_mul_u32_u24_e32 v2, 3, v2
	v_add_u32_e32 v2, v2, v1
	v_mul_u32_u24_e32 v0, 0x5556, v1
	v_lshrrev_b32_e32 v0, 16, v0
	v_mul_u32_u24_e32 v0, 45, v0
	v_add3_u32 v0, v0, v2, s101
	s_mov_b32 s8, 0xd5555555
	v_mul_hi_i32 v1, v0, s8
	v_lshrrev_b32_e32 v2, 31, v1
	v_ashrrev_i32_e32 v1, 3, v1
	s_movk_i32 s8, 0x7f
	v_add3_u32 v217, v1, v2, s8
	s_mov_b32 s8, 0x2aaaaaab
	v_mul_hi_i32 v1, v0, s8
	v_lshrrev_b32_e32 v2, 31, v1
	v_lshrrev_b32_e32 v1, 3, v1
	v_add_u32_e32 v1, v1, v2
	v_mul_lo_u32 v1, v1, 48
	v_sub_u32_e32 v0, v0, v1
	v_mul_lo_u16_e32 v1, 43, v0
	v_lshrrev_b16_e32 v2, 15, v1
	v_add_u16_sdwa v1, v1, v2 dst_sel:DWORD dst_unused:UNUSED_PAD src0_sel:BYTE_1 src1_sel:DWORD
	v_bfe_i32 v2, v1, 0, 8
	v_mul_lo_u16_e32 v1, 6, v1
	v_sub_u16_e32 v0, v0, v1
	v_bfe_i32 v28, v0, 0, 8
	v_mov_b32_e32 v0, v129
	v_lshlrev_b32_e32 v31, 5, v217
	v_and_b32_e32 v29, 31, v0
	v_bfe_u32 v30, v0, 5, 1
	v_mul_lo_u16_e32 v0, 0x56, v28
	v_lshrrev_b16_e32 v1, 15, v0
	v_add_u16_sdwa v0, v0, v1 dst_sel:DWORD dst_unused:UNUSED_PAD src0_sel:BYTE_1 src1_sel:DWORD
	v_readlane_b32 s8, v253, 13
	v_bfe_i32 v0, v0, 0, 8
	v_or_b32_e32 v10, v29, v31
	v_readlane_b32 s9, v253, 14
	v_lshl_add_u32 v8, v2, 1, v0
	v_lshl_add_u32 v22, v2, 12, v10
	v_mov_b64_e32 v[0:1], s[8:9]
	s_movk_i32 s23, 0x300
	v_mad_i64_i32 v[0:1], s[8:9], v22, s23, v[0:1]
	v_lshlrev_b32_e32 v2, 6, v28
	v_ashrrev_i32_e32 v3, 31, v2
	v_readlane_b32 s8, v253, 23
	v_lshlrev_b64 v[2:3], 1, v[2:3]
	v_readlane_b32 s9, v253, 24
	v_lshl_add_u64 v[4:5], v[0:1], 0, v[2:3]
	v_lshlrev_b32_e32 v130, 3, v30
	v_mov_b64_e32 v[0:1], s[8:9]
	v_mad_i64_i32 v[0:1], s[8:9], v22, s23, v[0:1]
	v_readlane_b32 s8, v253, 19
	v_readlane_b32 s9, v253, 20
	v_lshl_add_u64 v[0:1], v[0:1], 0, v[2:3]
	v_ashrrev_i32_e32 v9, 31, v8
	v_mov_b64_e32 v[6:7], s[8:9]
	s_movk_i32 s8, 0x600
	v_mad_i64_i32 v[6:7], s[8:9], v22, s8, v[6:7]
	v_lshl_add_u64 v[2:3], v[6:7], 0, v[2:3]
	v_lshl_add_u64 v[12:13], v[0:1], 0, v[130:131]
	v_readlane_b32 s8, v253, 25
	v_lshlrev_b32_e32 v0, 3, v29
	v_lshl_add_u64 v[132:133], v[2:3], 0, v[130:131]
	v_lshlrev_b64 v[14:15], 19, v[8:9]
	v_readlane_b32 s9, v253, 26
	v_lshl_or_b32 v130, v30, 8, v0
	v_lshlrev_b32_e32 v20, 1, v130
	v_lshl_add_u64 v[16:17], s[8:9], 0, v[14:15]
	v_mov_b32_e32 v21, v131
	v_lshl_add_u64 v[148:149], v[16:17], 0, v[20:21]
	global_load_dwordx4 v[0:3], v[148:149], off
	v_lshlrev_b32_e32 v6, 4, v30
	v_mov_b32_e32 v7, v131
	v_lshl_add_u64 v[4:5], v[4:5], 0, v[6:7]
	global_load_dwordx4 v[80:83], v[4:5], off
	v_mov_b64_e32 v[6:7], s[34:35]
	s_movk_i32 s8, 0x48
	v_mad_i64_i32 v[6:7], s[8:9], v22, s8, v[6:7]
	v_mul_i32_i24_e32 v22, 3, v28
	v_ashrrev_i32_e32 v23, 31, v22
	v_cmp_eq_u32_e32 vcc, 0, v217
	v_lshl_add_u64 v[6:7], v[22:23], 2, v[6:7]
	s_mov_b32 s8, 0x165c4000
	v_cndmask_b32_e64 v18, v197, 0, vcc
	v_add_co_u32_e32 v22, vcc, s8, v6
	v_readlane_b32 s8, v253, 21
	s_nop 0
	v_addc_co_u32_e32 v23, vcc, 0, v7, vcc
	global_load_dwordx4 v[84:87], v[4:5], off offset:32
	global_load_dwordx4 v[88:91], v[4:5], off offset:64
	global_load_dwordx4 v[92:95], v[4:5], off offset:96
	global_load_dwordx2 v[136:137], v[12:13], off offset:64
	global_load_dwordx2 v[144:145], v[12:13], off offset:80
	global_load_dwordx2 v[150:151], v[12:13], off offset:32
	global_load_dwordx2 v[160:161], v[12:13], off offset:48
	global_load_dwordx2 v[134:135], v[132:133], off
	global_load_dwordx2 v[142:143], v[132:133], off offset:16
	global_load_dwordx2 v[152:153], v[132:133], off offset:32
	global_load_dwordx2 v[162:163], v[132:133], off offset:48
	global_load_dwordx2 v[154:155], v[12:13], off offset:96
	global_load_dwordx2 v[164:165], v[12:13], off offset:112
	global_load_dwordx4 v[4:7], v[148:149], off offset:1024
	global_load_dwordx2 v[138:139], v[132:133], off offset:64
	global_load_dwordx2 v[146:147], v[132:133], off offset:80
	global_load_dwordx2 v[158:159], v[132:133], off offset:96
	global_load_dwordx2 v[166:167], v[132:133], off offset:112
	v_lshlrev_b64 v[8:9], 15, v[8:9]
	v_readlane_b32 s9, v253, 22
	v_mov_b32_e32 v11, v131
	v_mov_b32_e32 v19, v131
	v_lshl_add_u64 v[8:9], s[8:9], 0, v[8:9]
	v_lshl_add_u64 v[24:25], v[10:11], 3, v[8:9]
	v_lshl_add_u64 v[26:27], v[16:17], 0, v[18:19]
	global_load_dwordx4 v[8:11], v[148:149], off offset:2048
	global_load_dwordx2 v[168:169], v[24:25], off
	global_load_dword v218, v[22:23], off offset:4
	global_load_dwordx2 v[140:141], v[12:13], off
	global_load_dwordx2 v[156:157], v[12:13], off offset:16
	global_load_dwordx4 v[16:19], v[148:149], off offset:3072
	v_readlane_b32 s8, v253, 27
	v_readlane_b32 s9, v253, 28
	v_lshl_add_u64 v[12:13], v[26:27], 0, v[20:21]
	global_load_dwordx4 v[108:111], v[12:13], off offset:3072
	global_load_dwordx4 v[104:107], v[12:13], off offset:2048
	global_load_dwordx4 v[100:103], v[12:13], off offset:1024
	global_load_dwordx4 v[96:99], v[12:13], off
	v_lshl_add_u64 v[14:15], s[8:9], 0, v[14:15]
	v_lshl_add_u64 v[170:171], v[14:15], 0, v[130:131]
	global_load_dwordx2 v[114:115], v[170:171], off offset:3584
	global_load_dwordx2 v[112:113], v[170:171], off offset:3072
	global_load_dwordx2 v[118:119], v[170:171], off offset:2560
	global_load_dwordx2 v[116:117], v[170:171], off offset:2048
	global_load_dwordx2 v[122:123], v[170:171], off offset:1536
	global_load_dwordx2 v[120:121], v[170:171], off offset:1024
	global_load_dwordx2 v[126:127], v[170:171], off offset:512
	global_load_dwordx2 v[124:125], v[170:171], off
	s_mov_b32 s56, 0
	s_mov_b32 s57, s56
	s_mov_b32 s58, s56
	s_mov_b32 s59, s56
	s_mov_b32 s60, s56
	s_mov_b32 s61, s56
	s_mov_b32 s62, s56
	s_mov_b32 s63, s56
	s_mov_b32 s64, s56
	s_mov_b32 s65, s56
	s_mov_b32 s66, s56
	s_mov_b32 s67, s56
	s_mov_b32 s68, s56
	s_mov_b32 s69, s56
	s_waitcnt vmcnt(36)
; #define MFMA32(a, b, c) __builtin_amdgcn_mfma_f32_32x32x16_bf16((a), (b), (c), 0, 0, 0)
; template <class KP, class VP, class ACT, class FILL>
; DI void attn_loop(AttnSt& st, const bf16x8 (&qf)[4], int k0, int k1, size_t vstride, KP kp, VP vp, ACT act, FILL fill) {
;     ...
;   for (int kt = k0; kt <= k1; ++kt) {
;     const int kn = (kt < k1) ? kt + 1 : k1;
;     const int kn2 = (kt + 2 <= k1) ? kt + 2 : k1;
;     {
;       const bf16_t* v0 = vp(kn);
; #pragma unroll
;       for (int j = 0; j < 8; ++j) nxt.v[j] = *(const s16x4*)(v0 + 256 * j);
;     }
;     bf16x8 k2[4];
;     {
;       const bf16_t* krow = kp(kn2);
; #pragma unroll
;       for (int ss = 0; ss < 4; ++ss) k2[ss] = *(const bf16x8*)(krow + 512 * ss);
;     }
;     f32x16 s_next;
; #pragma unroll
;     for (int i = 0; i < 16; ++i) s_next[i] = 0.f;
; #pragma unroll
;     for (int ss = 0; ss < 4; ++ss) s_next = MFMA32(nxt.k[ss], qf[ss], s_next);
; DI void bias16(const unsigned char* blut, const float* tblh, const int (&dist)[16], float (&bv)[16]) {
;   int bk[16];
; #pragma unroll
;   for (int i = 0; i < 16; ++i) { const int d = dist[i] < 0 ? 0 : (dist[i] > 2048 ? 2048 : dist[i]); bk[i] = blut[d]; }
; #pragma unroll
;   for (int i = 0; i < 16; ++i) asm volatile("" : "+v"(bk[i]));
; #pragma unroll
;   for (int i = 0; i < 16; ++i) bv[i] = tblh[bk[i]];
; #pragma unroll
;   for (int i = 0; i < 16; ++i) asm volatile("" : "+v"(bv[i]));
; }
	v_mfma_f32_32x32x16_bf16 v[48:63], v[0:3], v[80:83], 0
	s_mov_b32 s70, s56
	s_mov_b32 s71, s56
	v_lshlrev_b32_e32 v20, 2, v30
	v_lshl_add_u32 v219, v28, 7, 0
	v_subrev_u32_e32 v220, 31, v31
	v_sub_u32_e32 v221, v29, v20
	v_mov_b32_e32 v222, 0
	s_waitcnt vmcnt(22)
	v_mfma_f32_32x32x16_bf16 v[48:63], v[4:7], v[84:87], v[48:63]
	v_mov_b32_e32 v223, 0xff800000
	s_waitcnt vmcnt(17)
	v_mfma_f32_32x32x16_bf16 v[48:63], v[8:11], v[88:91], v[48:63]
	v_mov_b64_e32 v[0:1], s[56:57]
	v_mov_b64_e32 v[14:15], s[70:71]
	v_mov_b64_e32 v[2:3], s[58:59]
	v_mov_b64_e32 v[4:5], s[60:61]
	v_mov_b64_e32 v[6:7], s[62:63]
	v_mov_b64_e32 v[8:9], s[64:65]
	v_mov_b64_e32 v[10:11], s[66:67]
	s_waitcnt vmcnt(12)
	v_mfma_f32_32x32x16_bf16 v[48:63], v[16:19], v[92:95], v[48:63]
	v_mov_b64_e32 v[12:13], s[68:69]
	v_mov_b64_e32 v[30:31], v[14:15]
	s_mov_b64 s[58:59], 0
	v_mov_b64_e32 v[28:29], v[12:13]
	v_mov_b64_e32 v[26:27], v[10:11]
	v_mov_b64_e32 v[24:25], v[8:9]
	v_mov_b64_e32 v[22:23], v[6:7]
	v_mov_b64_e32 v[20:21], v[4:5]
	v_mov_b64_e32 v[18:19], v[2:3]
	v_mov_b64_e32 v[16:17], v[0:1]
	s_waitcnt vmcnt(0)
	v_readfirstlane_b32 s60, v217
	v_lshrrev_b32_e32 v246, 6, v129
	v_and_b32_e32 v247, 63, v129
	v_lshlrev_b32_e32 v247, 3, v247
	v_readfirstlane_b32 s58, v246
	v_mov_b32_e32 v224, s60
	v_mov_b32_e32 v225, 0x1940
	v_lshl_add_u32 v234, v246, 2, v225
	ds_write_b32 v234, v224
	s_waitcnt lgkmcnt(0)
	s_barrier
	ds_read_b128 v[226:229], v225
	ds_read_b128 v[230:233], v225 offset:16
	s_waitcnt lgkmcnt(0)
	v_max3_u32 v226, v226, v227, v228
	v_max3_u32 v226, v226, v229, v230
	v_max3_u32 v226, v226, v231, v232
	v_max_u32_e32 v226, v226, v233
	s_nop 0
	v_readfirstlane_b32 s59, v226
	s_mov_b32 s56, 0
	s_mov_b32 s23, 0
	s_mov_b32 s100, 0x10000
	s_lshr_b32 s24, s59, 1
	s_min_u32 s24, s23, s24
	s_lshl_b32 s26, s24, 13
	s_lshl_b32 s24, s58, 10
	s_add_u32 s26, s26, s24
	s_mov_b32 s27, 0
	v_lshl_add_u64 v[248:249], v[148:149], 0, s[26:27]
	v_lshl_add_u64 v[250:251], v[170:171], 0, s[26:27]
	v_add_co_u32_e32 v250, vcc, v250, v247
	v_addc_co_u32_e32 v251, vcc, 0, v251, vcc
	s_add_u32 s24, s24, s100
	s_mov_b32 m0, s24
	s_nop 0
	global_load_lds_dwordx4 v[248:249], off
	s_add_u32 s24, s24, 0x2000
	s_mov_b32 m0, s24
	s_nop 0
	global_load_lds_dwordx4 v[250:251], off
	s_mov_b32 s23, 1
	s_mov_b32 s100, 0x14000
	s_lshr_b32 s24, s59, 1
	s_min_u32 s24, s23, s24
	s_lshl_b32 s26, s24, 13
	s_lshl_b32 s24, s58, 10
	s_add_u32 s26, s26, s24
	s_mov_b32 s27, 0
	v_lshl_add_u64 v[248:249], v[148:149], 0, s[26:27]
	v_lshl_add_u64 v[250:251], v[170:171], 0, s[26:27]
	v_add_co_u32_e32 v250, vcc, v250, v247
	v_addc_co_u32_e32 v251, vcc, 0, v251, vcc
	s_add_u32 s24, s24, s100
	s_mov_b32 m0, s24
	s_nop 0
	global_load_lds_dwordx4 v[248:249], off
	s_add_u32 s24, s24, 0x2000
	s_mov_b32 m0, s24
	s_nop 0
	global_load_lds_dwordx4 v[250:251], off
	s_mov_b32 s100, 0x10000
	v_lshrrev_b32_e32 v246, 6, v129
	v_mul_u32_u24_e32 v246, 6912, v246
	v_add_u32_e32 v242, 8192, v246
	v_and_b32_e32 v246, 63, v129
	v_mov_b32_e32 v96, 0
	v_mov_b32_e32 v97, v246
	v_add_u32_e32 v98, 64, v246
	v_add_u32_e32 v99, 128, v246
	v_add_u32_e32 v100, 192, v246
	v_add_u32_e32 v101, 256, v246
	v_add_u32_e32 v102, 320, v246
	v_add_u32_e32 v103, 384, v246
	v_add_u32_e32 v104, 448, v246
	v_add_u32_e32 v105, 512, v246
	v_add_u32_e32 v106, 576, v246
	v_add_u32_e32 v107, 640, v246
	v_add_u32_e32 v108, 704, v246
	v_add_u32_e32 v109, 768, v246
	v_add_u32_e32 v110, 832, v246
	v_add_u32_e32 v111, 896, v246
	v_add_u32_e32 v112, 960, v246
	v_add_u32_e32 v113, 1024, v246
	v_add_u32_e32 v114, 1088, v246
	v_add_u32_e32 v115, 1152, v246
	v_add_u32_e32 v116, 1216, v246
	v_add_u32_e32 v117, 1280, v246
	v_add_u32_e32 v118, 1344, v246
	v_add_u32_e32 v119, 1408, v246
	v_add_u32_e32 v120, 1472, v246
	v_add_u32_e32 v121, 1536, v246
	v_add_u32_e32 v122, 1600, v246
	ds_read_u8 v96, v96
	ds_read_u8 v97, v97
	ds_read_u8 v98, v98
	ds_read_u8 v99, v99
	ds_read_u8 v100, v100
	ds_read_u8 v101, v101
	ds_read_u8 v102, v102
	ds_read_u8 v103, v103
	ds_read_u8 v104, v104
	ds_read_u8 v105, v105
	ds_read_u8 v106, v106
	ds_read_u8 v107, v107
	ds_read_u8 v108, v108
	ds_read_u8 v109, v109
	ds_read_u8 v110, v110
	ds_read_u8 v111, v111
	ds_read_u8 v112, v112
	ds_read_u8 v113, v113
	ds_read_u8 v114, v114
	ds_read_u8 v115, v115
	ds_read_u8 v116, v116
	ds_read_u8 v117, v117
	ds_read_u8 v118, v118
	ds_read_u8 v119, v119
	ds_read_u8 v120, v120
	ds_read_u8 v121, v121
	ds_read_u8 v122, v122
	s_waitcnt lgkmcnt(15)
; DI void bias16(const unsigned char* blut, const float* tblh, const int (&dist)[16], float (&bv)[16]) {
;   int bk[16];
; #pragma unroll
;   for (int i = 0; i < 16; ++i) { const int d = dist[i] < 0 ? 0 : (dist[i] > 2048 ? 2048 : dist[i]); bk[i] = blut[d]; }
; #pragma unroll
;   for (int i = 0; i < 16; ++i) asm volatile("" : "+v"(bk[i]));
; #pragma unroll
;   for (int i = 0; i < 16; ++i) bv[i] = tblh[bk[i]];
; #pragma unroll
;   for (int i = 0; i < 16; ++i) asm volatile("" : "+v"(bv[i]));
; }
	v_lshl_add_u32 v96, v96, 2, v219
	s_waitcnt lgkmcnt(15)
	v_lshl_add_u32 v97, v97, 2, v219
	s_waitcnt lgkmcnt(15)
	v_lshl_add_u32 v98, v98, 2, v219
	s_waitcnt lgkmcnt(15)
	v_lshl_add_u32 v99, v99, 2, v219
	s_waitcnt lgkmcnt(15)
	v_lshl_add_u32 v100, v100, 2, v219
	s_waitcnt lgkmcnt(15)
	v_lshl_add_u32 v101, v101, 2, v219
	s_waitcnt lgkmcnt(15)
	v_lshl_add_u32 v102, v102, 2, v219
	s_waitcnt lgkmcnt(15)
	v_lshl_add_u32 v103, v103, 2, v219
	s_waitcnt lgkmcnt(15)
	v_lshl_add_u32 v104, v104, 2, v219
	s_waitcnt lgkmcnt(15)
	v_lshl_add_u32 v105, v105, 2, v219
	s_waitcnt lgkmcnt(15)
	v_lshl_add_u32 v106, v106, 2, v219
	s_waitcnt lgkmcnt(15)
	v_lshl_add_u32 v107, v107, 2, v219
	s_waitcnt lgkmcnt(14)
	v_lshl_add_u32 v108, v108, 2, v219
	s_waitcnt lgkmcnt(13)
	v_lshl_add_u32 v109, v109, 2, v219
	s_waitcnt lgkmcnt(12)
	v_lshl_add_u32 v110, v110, 2, v219
	s_waitcnt lgkmcnt(11)
	v_lshl_add_u32 v111, v111, 2, v219
	s_waitcnt lgkmcnt(10)
	v_lshl_add_u32 v112, v112, 2, v219
	s_waitcnt lgkmcnt(9)
	v_lshl_add_u32 v113, v113, 2, v219
	s_waitcnt lgkmcnt(8)
	v_lshl_add_u32 v114, v114, 2, v219
	s_waitcnt lgkmcnt(7)
	v_lshl_add_u32 v115, v115, 2, v219
	s_waitcnt lgkmcnt(6)
	v_lshl_add_u32 v116, v116, 2, v219
	s_waitcnt lgkmcnt(5)
	v_lshl_add_u32 v117, v117, 2, v219
	s_waitcnt lgkmcnt(4)
	v_lshl_add_u32 v118, v118, 2, v219
	s_waitcnt lgkmcnt(3)
	v_lshl_add_u32 v119, v119, 2, v219
	s_waitcnt lgkmcnt(2)
	v_lshl_add_u32 v120, v120, 2, v219
	s_waitcnt lgkmcnt(1)
	v_lshl_add_u32 v121, v121, 2, v219
	s_waitcnt lgkmcnt(0)
	v_lshl_add_u32 v122, v122, 2, v219
	ds_read_b32 v96, v96 offset:4096
	ds_read_b32 v97, v97 offset:4096
	ds_read_b32 v98, v98 offset:4096
	ds_read_b32 v99, v99 offset:4096
	ds_read_b32 v100, v100 offset:4096
	ds_read_b32 v101, v101 offset:4096
	ds_read_b32 v102, v102 offset:4096
	ds_read_b32 v103, v103 offset:4096
	ds_read_b32 v104, v104 offset:4096
	ds_read_b32 v105, v105 offset:4096
	ds_read_b32 v106, v106 offset:4096
	ds_read_b32 v107, v107 offset:4096
	ds_read_b32 v108, v108 offset:4096
	ds_read_b32 v109, v109 offset:4096
	ds_read_b32 v110, v110 offset:4096
	ds_read_b32 v111, v111 offset:4096
	ds_read_b32 v112, v112 offset:4096
	ds_read_b32 v113, v113 offset:4096
	ds_read_b32 v114, v114 offset:4096
	ds_read_b32 v115, v115 offset:4096
	ds_read_b32 v116, v116 offset:4096
	ds_read_b32 v117, v117 offset:4096
	ds_read_b32 v118, v118 offset:4096
	ds_read_b32 v119, v119 offset:4096
	ds_read_b32 v120, v120 offset:4096
	ds_read_b32 v121, v121 offset:4096
	ds_read_b32 v122, v122 offset:4096
	v_lshl_add_u32 v244, v246, 2, v242
	s_waitcnt lgkmcnt(15)
	ds_write_b32 v244, v96 offset:0
	s_waitcnt lgkmcnt(15)
	ds_write_b32 v244, v97 offset:256
	s_waitcnt lgkmcnt(15)
	ds_write_b32 v244, v98 offset:512
	s_waitcnt lgkmcnt(15)
	ds_write_b32 v244, v99 offset:768
	s_waitcnt lgkmcnt(15)
	ds_write_b32 v244, v100 offset:1024
	s_waitcnt lgkmcnt(15)
	ds_write_b32 v244, v101 offset:1280
	s_waitcnt lgkmcnt(15)
	ds_write_b32 v244, v102 offset:1536
	s_waitcnt lgkmcnt(15)
	ds_write_b32 v244, v103 offset:1792
	s_waitcnt lgkmcnt(15)
	ds_write_b32 v244, v104 offset:2048
	s_waitcnt lgkmcnt(15)
	ds_write_b32 v244, v105 offset:2304
	s_waitcnt lgkmcnt(15)
	ds_write_b32 v244, v106 offset:2560
	s_waitcnt lgkmcnt(15)
	ds_write_b32 v244, v107 offset:2816
	s_waitcnt lgkmcnt(15)
	ds_write_b32 v244, v108 offset:3072
	s_waitcnt lgkmcnt(15)
	ds_write_b32 v244, v109 offset:3328
	s_waitcnt lgkmcnt(15)
	ds_write_b32 v244, v110 offset:3584
	s_waitcnt lgkmcnt(15)
	ds_write_b32 v244, v111 offset:3840
	s_waitcnt lgkmcnt(15)
	ds_write_b32 v244, v112 offset:4096
	s_waitcnt lgkmcnt(15)
	ds_write_b32 v244, v113 offset:4352
	s_waitcnt lgkmcnt(15)
	ds_write_b32 v244, v114 offset:4608
	s_waitcnt lgkmcnt(15)
	ds_write_b32 v244, v115 offset:4864
	s_waitcnt lgkmcnt(15)
	ds_write_b32 v244, v116 offset:5120
	s_waitcnt lgkmcnt(15)
	ds_write_b32 v244, v117 offset:5376
	s_waitcnt lgkmcnt(15)
	ds_write_b32 v244, v118 offset:5632
	s_waitcnt lgkmcnt(15)
	ds_write_b32 v244, v119 offset:5888
	s_waitcnt lgkmcnt(15)
	ds_write_b32 v244, v120 offset:6144
	s_waitcnt lgkmcnt(15)
	ds_write_b32 v244, v121 offset:6400
	s_waitcnt lgkmcnt(15)
	ds_write_b32 v244, v122 offset:6656
	ds_read_b32 v240, v219 offset:4220
	v_add_u32_e32 v242, 148, v242
	v_mov_b32_e32 v243, 0x7f800000
	s_waitcnt lgkmcnt(0)

; #define MFMA32(a, b, c) __builtin_amdgcn_mfma_f32_32x32x16_bf16((a), (b), (c), 0, 0, 0)
; #define NEGINF (-__builtin_inff())
; DI float shx32(float v) { const auto r = __builtin_amdgcn_permlane32_swap(__float_as_uint(v), __float_as_uint(v), false, false); return __uint_as_float((threadIdx.x & 32) ? r[0] : r[1]); }
; DI void bias16(const unsigned char* blut, const float* tblh, const int (&dist)[16], float (&bv)[16]) {
;   int bk[16];
; #pragma unroll
;   for (int i = 0; i < 16; ++i) { const int d = dist[i] < 0 ? 0 : (dist[i] > 2048 ? 2048 : dist[i]); bk[i] = blut[d]; }
; #pragma unroll
;   for (int i = 0; i < 16; ++i) asm volatile("" : "+v"(bk[i]));
; #pragma unroll
;   for (int i = 0; i < 16; ++i) bv[i] = tblh[bk[i]];
; #pragma unroll
;   for (int i = 0; i < 16; ++i) asm volatile("" : "+v"(bv[i]));
; }
; DI void moba_item(const Params& p, int b, int hd, int qb, const unsigned char* blut, const float* tbl) {
;     ...
;   unsigned mmask = 0u;
;   if (c > 0) {
;     const bf16_t* km = (const bf16_t*)(p.ws + OFF_KMEAN) + (size_t)bh * 16 * 64 + (size_t)(r & 15) * 64 + 8 * h;
;     f32x16 s;
; #pragma unroll
;     for (int i = 0; i < 16; ++i) s[i] = 0.f;
; #pragma unroll
;     for (int ss = 0; ss < 4; ++ss) {
;       bf16x8 kf = *(const bf16x8*)(km + 16 * ss);
;       if (r >= 16) {
; #pragma unroll
;         for (int j = 0; j < 8; ++j) kf[j] = 0;
;       }
;       s = MFMA32(kf, qf[ss], s);
;     }
;     float g16[16];
; #pragma unroll
;     for (int i = 0; i < 8; ++i) {
;       const float own = s[i], oth = shx32(own);
;       const int base = (i & 3) + 8 * (i >> 2);
;       g16[base] = h ? oth : own;
;       g16[base + 4] = h ? own : oth;
;     }
; #pragma unroll
;     for (int n = 0; n < 16; ++n) g16[n] = (n < c) ? g16[n] : NEGINF;
; #pragma unroll
;     for (int round = 0; round < 3; ++round) {
;       float best = NEGINF; int bi = -1;
; #pragma unroll
;       for (int n = 0; n < 16; ++n) if (g16[n] > best) { best = g16[n]; bi = n; }
;       if (bi >= 0) mmask |= 1u << bi;
; #pragma unroll
;       for (int n = 0; n < 16; ++n) if (n == bi) g16[n] = NEGINF;
;     }
;   }
;   mmask |= 1u << c;
;   const bf16_t* K = (const bf16_t*)(p.ws + OFF_KM) + (size_t)bh * 4096 * 64;
;   const bf16_t* Vt = (const bf16_t*)(p.ws + OFF_VMT) + (size_t)bh * 64 * 4096;
;   AttnSt st; attn_init(st);
;   attn_loop(st, qf, 0, qb, 32,
.LBB0_942:
	s_andn2_saveexec_b64 s[8:9], s[8:9]
	v_mov_b32_e32 v0, 0
	s_or_b64 exec, exec, s[8:9]
	v_readlane_b32 s8, v253, 49
	v_lshlrev_b32_e32 v1, 3, v18
	v_lshlrev_b64 v[14:15], 19, v[16:17]
	v_readlane_b32 s9, v253, 50
	v_lshl_or_b32 v130, v19, 8, v1
	v_lshlrev_b32_e32 v26, 1, v130
	v_lshl_add_u64 v[16:17], s[8:9], 0, v[14:15]
	v_mov_b32_e32 v27, v131
	v_lshl_add_u64 v[134:135], v[16:17], 0, v[26:27]
	global_load_dwordx4 v[2:5], v[134:135], off
	global_load_dwordx4 v[6:9], v[134:135], off offset:1024
	global_load_dwordx4 v[10:13], v[134:135], off offset:2048
	global_load_dwordx4 v[22:25], v[134:135], off offset:3072
	v_readlane_b32 s8, v253, 51
	v_cmp_eq_u32_e32 vcc, 0, v154
	v_readlane_b32 s9, v253, 52
	v_mov_b32_e32 v29, v131
	v_cndmask_b32_e64 v28, v197, 0, vcc
	v_lshl_add_u64 v[14:15], s[8:9], 0, v[14:15]
	v_lshl_add_u64 v[16:17], v[16:17], 0, v[28:29]
	v_lshl_add_u64 v[16:17], v[16:17], 0, v[26:27]
	v_lshl_add_u64 v[136:137], v[14:15], 0, v[130:131]
	global_load_dwordx4 v[108:111], v[16:17], off offset:3072
	global_load_dwordx4 v[104:107], v[16:17], off offset:2048
	global_load_dwordx4 v[100:103], v[16:17], off offset:1024
	global_load_dwordx4 v[96:99], v[16:17], off
	global_load_dwordx2 v[114:115], v[136:137], off offset:3584
	global_load_dwordx2 v[112:113], v[136:137], off offset:3072
	global_load_dwordx2 v[118:119], v[136:137], off offset:2560
	global_load_dwordx2 v[116:117], v[136:137], off offset:2048
	global_load_dwordx2 v[122:123], v[136:137], off offset:1536
	global_load_dwordx2 v[120:121], v[136:137], off offset:1024
	global_load_dwordx2 v[126:127], v[136:137], off offset:512
	global_load_dwordx2 v[124:125], v[136:137], off
	s_mov_b32 s56, 0
	v_lshrrev_b32_e32 v1, 3, v154
	s_mov_b32 s57, s56
	v_lshl_or_b32 v157, 1, v1, v0
	s_mov_b32 s58, s56
	s_mov_b32 s59, s56
	s_mov_b32 s60, s56
	s_mov_b32 s61, s56
	s_mov_b32 s62, s56
	s_mov_b32 s63, s56
	s_mov_b32 s64, s56
	s_mov_b32 s65, s56
	s_mov_b32 s66, s56
	s_mov_b32 s67, s56
	s_mov_b32 s68, s56
	s_mov_b32 s69, s56
	s_mov_b32 s70, s56
	s_mov_b32 s71, s56
	v_sub_u32_e32 v16, 0, v21
	v_lshlrev_b32_e32 v155, 2, v19
	v_lshlrev_b32_e32 v133, 6, v20
	v_lshl_add_u32 v156, v20, 7, 0
	v_sub_u32_e32 v158, v18, v155
	v_lshl_add_u32 v159, v16, 5, v208
	v_mov_b32_e32 v160, 0
	v_mov_b32_e32 v161, 0xff800000
	s_waitcnt vmcnt(15)
	v_mfma_f32_32x32x16_bf16 v[48:63], v[2:5], v[80:83], 0
	s_waitcnt vmcnt(14)
	v_mfma_f32_32x32x16_bf16 v[48:63], v[6:9], v[84:87], v[48:63]
	s_waitcnt vmcnt(13)
	v_mfma_f32_32x32x16_bf16 v[48:63], v[10:13], v[88:91], v[48:63]
	v_mov_b64_e32 v[0:1], s[56:57]
	v_mov_b64_e32 v[14:15], s[70:71]
	v_mov_b64_e32 v[2:3], s[58:59]
	v_mov_b64_e32 v[4:5], s[60:61]
	v_mov_b64_e32 v[6:7], s[62:63]
	v_mov_b64_e32 v[8:9], s[64:65]
	v_mov_b64_e32 v[10:11], s[66:67]
	s_waitcnt vmcnt(12)
	v_mfma_f32_32x32x16_bf16 v[48:63], v[22:25], v[92:95], v[48:63]
	v_mov_b64_e32 v[12:13], s[68:69]
	v_mov_b64_e32 v[30:31], v[14:15]
	s_mov_b64 s[58:59], 0
	v_mov_b64_e32 v[28:29], v[12:13]
	v_mov_b64_e32 v[26:27], v[10:11]
	v_mov_b64_e32 v[24:25], v[8:9]
	v_mov_b64_e32 v[22:23], v[6:7]
	v_mov_b64_e32 v[20:21], v[4:5]
	v_mov_b64_e32 v[18:19], v[2:3]
	v_mov_b64_e32 v[16:17], v[0:1]
	s_waitcnt vmcnt(0)
	v_readfirstlane_b32 s60, v154
	v_lshrrev_b32_e32 v184, 6, v129
	v_and_b32_e32 v185, 63, v129
	v_lshlrev_b32_e32 v185, 3, v185
	v_readfirstlane_b32 s58, v184
	v_mov_b32_e32 v162, s60
	v_mov_b32_e32 v163, 0x1940
	v_lshl_add_u32 v172, v184, 2, v163
	ds_write_b32 v172, v162
	s_waitcnt lgkmcnt(0)
	s_barrier
	ds_read_b128 v[164:167], v163
	ds_read_b128 v[168:171], v163 offset:16
	s_waitcnt lgkmcnt(0)
	v_max3_u32 v164, v164, v165, v166
	v_max3_u32 v164, v164, v167, v168
	v_max3_u32 v164, v164, v169, v170
	v_max_u32_e32 v164, v164, v171
	s_nop 0
	v_readfirstlane_b32 s59, v164
	s_mov_b32 s56, 0
	s_mov_b32 s23, 0
	s_mov_b32 s100, 0x10000
	s_lshr_b32 s24, s59, 1
	s_min_u32 s24, s23, s24
	s_lshl_b32 s26, s24, 13
	s_lshl_b32 s24, s58, 10
	s_add_u32 s26, s26, s24
	s_mov_b32 s27, 0
	v_lshl_add_u64 v[186:187], v[134:135], 0, s[26:27]
	v_lshl_add_u64 v[218:219], v[136:137], 0, s[26:27]
	v_add_co_u32_e32 v218, vcc, v218, v185
	v_addc_co_u32_e32 v219, vcc, 0, v219, vcc
	s_add_u32 s24, s24, s100
	s_mov_b32 m0, s24
	s_nop 0
	global_load_lds_dwordx4 v[186:187], off
	s_add_u32 s24, s24, 0x2000
	s_mov_b32 m0, s24
	s_nop 0
	global_load_lds_dwordx4 v[218:219], off
	s_mov_b32 s23, 1
	s_mov_b32 s100, 0x14000
	s_lshr_b32 s24, s59, 1
	s_min_u32 s24, s23, s24
	s_lshl_b32 s26, s24, 13
	s_lshl_b32 s24, s58, 10
	s_add_u32 s26, s26, s24
	s_mov_b32 s27, 0
	v_lshl_add_u64 v[186:187], v[134:135], 0, s[26:27]
	v_lshl_add_u64 v[218:219], v[136:137], 0, s[26:27]
	v_add_co_u32_e32 v218, vcc, v218, v185
	v_addc_co_u32_e32 v219, vcc, 0, v219, vcc
	s_add_u32 s24, s24, s100
	s_mov_b32 m0, s24
	s_nop 0
	global_load_lds_dwordx4 v[186:187], off
	s_add_u32 s24, s24, 0x2000
	s_mov_b32 m0, s24
	s_nop 0
	global_load_lds_dwordx4 v[218:219], off
	s_mov_b32 s100, 0x10000
	v_lshrrev_b32_e32 v184, 6, v129
	v_mul_u32_u24_e32 v184, 6912, v184
	v_add_u32_e32 v180, 8192, v184
	v_and_b32_e32 v184, 63, v129
	v_mov_b32_e32 v96, 0
	v_mov_b32_e32 v97, v184
	v_add_u32_e32 v98, 64, v184
	v_add_u32_e32 v99, 128, v184
	v_add_u32_e32 v100, 192, v184
	v_add_u32_e32 v101, 256, v184
	v_add_u32_e32 v102, 320, v184
	v_add_u32_e32 v103, 384, v184
	v_add_u32_e32 v104, 448, v184
	v_add_u32_e32 v105, 512, v184
	v_add_u32_e32 v106, 576, v184
	v_add_u32_e32 v107, 640, v184
	v_add_u32_e32 v108, 704, v184
	v_add_u32_e32 v109, 768, v184
	v_add_u32_e32 v110, 832, v184
	v_add_u32_e32 v111, 896, v184
	v_add_u32_e32 v112, 960, v184
	v_add_u32_e32 v113, 1024, v184
	v_add_u32_e32 v114, 1088, v184
	v_add_u32_e32 v115, 1152, v184
	v_add_u32_e32 v116, 1216, v184
	v_add_u32_e32 v117, 1280, v184
	v_add_u32_e32 v118, 1344, v184
	v_add_u32_e32 v119, 1408, v184
	v_add_u32_e32 v120, 1472, v184
	v_add_u32_e32 v121, 1536, v184
	v_add_u32_e32 v122, 1600, v184
	ds_read_u8 v96, v96
	ds_read_u8 v97, v97
	ds_read_u8 v98, v98
	ds_read_u8 v99, v99
	ds_read_u8 v100, v100
	ds_read_u8 v101, v101
	ds_read_u8 v102, v102
	ds_read_u8 v103, v103
	ds_read_u8 v104, v104
	ds_read_u8 v105, v105
	ds_read_u8 v106, v106
	ds_read_u8 v107, v107
	ds_read_u8 v108, v108
	ds_read_u8 v109, v109
	ds_read_u8 v110, v110
	ds_read_u8 v111, v111
	ds_read_u8 v112, v112
	ds_read_u8 v113, v113
	ds_read_u8 v114, v114
	ds_read_u8 v115, v115
	ds_read_u8 v116, v116
	ds_read_u8 v117, v117
	ds_read_u8 v118, v118
	ds_read_u8 v119, v119
	ds_read_u8 v120, v120
	ds_read_u8 v121, v121
	ds_read_u8 v122, v122
	s_waitcnt lgkmcnt(15)
; DI void bias16(const unsigned char* blut, const float* tblh, const int (&dist)[16], float (&bv)[16]) {
;   int bk[16];
; #pragma unroll
;   for (int i = 0; i < 16; ++i) { const int d = dist[i] < 0 ? 0 : (dist[i] > 2048 ? 2048 : dist[i]); bk[i] = blut[d]; }
; #pragma unroll
;   for (int i = 0; i < 16; ++i) asm volatile("" : "+v"(bk[i]));
; #pragma unroll
;   for (int i = 0; i < 16; ++i) bv[i] = tblh[bk[i]];
; #pragma unroll
;   for (int i = 0; i < 16; ++i) asm volatile("" : "+v"(bv[i]));
; }
	v_lshl_add_u32 v96, v96, 2, v156
	s_waitcnt lgkmcnt(15)
	v_lshl_add_u32 v97, v97, 2, v156
	s_waitcnt lgkmcnt(15)
	v_lshl_add_u32 v98, v98, 2, v156
	s_waitcnt lgkmcnt(15)
	v_lshl_add_u32 v99, v99, 2, v156
	s_waitcnt lgkmcnt(15)
	v_lshl_add_u32 v100, v100, 2, v156
	s_waitcnt lgkmcnt(15)
	v_lshl_add_u32 v101, v101, 2, v156
	s_waitcnt lgkmcnt(15)
	v_lshl_add_u32 v102, v102, 2, v156
	s_waitcnt lgkmcnt(15)
	v_lshl_add_u32 v103, v103, 2, v156
	s_waitcnt lgkmcnt(15)
	v_lshl_add_u32 v104, v104, 2, v156
	s_waitcnt lgkmcnt(15)
	v_lshl_add_u32 v105, v105, 2, v156
	s_waitcnt lgkmcnt(15)
	v_lshl_add_u32 v106, v106, 2, v156
	s_waitcnt lgkmcnt(15)
	v_lshl_add_u32 v107, v107, 2, v156
	s_waitcnt lgkmcnt(14)
	v_lshl_add_u32 v108, v108, 2, v156
	s_waitcnt lgkmcnt(13)
	v_lshl_add_u32 v109, v109, 2, v156
	s_waitcnt lgkmcnt(12)
	v_lshl_add_u32 v110, v110, 2, v156
	s_waitcnt lgkmcnt(11)
	v_lshl_add_u32 v111, v111, 2, v156
	s_waitcnt lgkmcnt(10)
	v_lshl_add_u32 v112, v112, 2, v156
	s_waitcnt lgkmcnt(9)
	v_lshl_add_u32 v113, v113, 2, v156
	s_waitcnt lgkmcnt(8)
	v_lshl_add_u32 v114, v114, 2, v156
	s_waitcnt lgkmcnt(7)
	v_lshl_add_u32 v115, v115, 2, v156
	s_waitcnt lgkmcnt(6)
	v_lshl_add_u32 v116, v116, 2, v156
	s_waitcnt lgkmcnt(5)
	v_lshl_add_u32 v117, v117, 2, v156
	s_waitcnt lgkmcnt(4)
	v_lshl_add_u32 v118, v118, 2, v156
	s_waitcnt lgkmcnt(3)
	v_lshl_add_u32 v119, v119, 2, v156
	s_waitcnt lgkmcnt(2)
	v_lshl_add_u32 v120, v120, 2, v156
	s_waitcnt lgkmcnt(1)
	v_lshl_add_u32 v121, v121, 2, v156
	s_waitcnt lgkmcnt(0)
	v_lshl_add_u32 v122, v122, 2, v156
	ds_read_b32 v96, v96 offset:4864
	ds_read_b32 v97, v97 offset:4864
	ds_read_b32 v98, v98 offset:4864
	ds_read_b32 v99, v99 offset:4864
	ds_read_b32 v100, v100 offset:4864
	ds_read_b32 v101, v101 offset:4864
	ds_read_b32 v102, v102 offset:4864
	ds_read_b32 v103, v103 offset:4864
	ds_read_b32 v104, v104 offset:4864
	ds_read_b32 v105, v105 offset:4864
	ds_read_b32 v106, v106 offset:4864
	ds_read_b32 v107, v107 offset:4864
	ds_read_b32 v108, v108 offset:4864
	ds_read_b32 v109, v109 offset:4864
	ds_read_b32 v110, v110 offset:4864
	ds_read_b32 v111, v111 offset:4864
	ds_read_b32 v112, v112 offset:4864
	ds_read_b32 v113, v113 offset:4864
	ds_read_b32 v114, v114 offset:4864
	ds_read_b32 v115, v115 offset:4864
	ds_read_b32 v116, v116 offset:4864
	ds_read_b32 v117, v117 offset:4864
	ds_read_b32 v118, v118 offset:4864
	ds_read_b32 v119, v119 offset:4864
	ds_read_b32 v120, v120 offset:4864
	ds_read_b32 v121, v121 offset:4864
	ds_read_b32 v122, v122 offset:4864
	v_lshl_add_u32 v182, v184, 2, v180
	s_waitcnt lgkmcnt(15)
	ds_write_b32 v182, v96 offset:0
	s_waitcnt lgkmcnt(15)
	ds_write_b32 v182, v97 offset:256
	s_waitcnt lgkmcnt(15)
	ds_write_b32 v182, v98 offset:512
	s_waitcnt lgkmcnt(15)
	ds_write_b32 v182, v99 offset:768
	s_waitcnt lgkmcnt(15)
	ds_write_b32 v182, v100 offset:1024
	s_waitcnt lgkmcnt(15)
	ds_write_b32 v182, v101 offset:1280
	s_waitcnt lgkmcnt(15)
	ds_write_b32 v182, v102 offset:1536
	s_waitcnt lgkmcnt(15)
	ds_write_b32 v182, v103 offset:1792
	s_waitcnt lgkmcnt(15)
	ds_write_b32 v182, v104 offset:2048
	s_waitcnt lgkmcnt(15)
	ds_write_b32 v182, v105 offset:2304
	s_waitcnt lgkmcnt(15)
	ds_write_b32 v182, v106 offset:2560
	s_waitcnt lgkmcnt(15)
	ds_write_b32 v182, v107 offset:2816
	s_waitcnt lgkmcnt(15)
	ds_write_b32 v182, v108 offset:3072
	s_waitcnt lgkmcnt(15)
	ds_write_b32 v182, v109 offset:3328
	s_waitcnt lgkmcnt(15)
	ds_write_b32 v182, v110 offset:3584
	s_waitcnt lgkmcnt(15)
	ds_write_b32 v182, v111 offset:3840
	s_waitcnt lgkmcnt(15)
	ds_write_b32 v182, v112 offset:4096
	s_waitcnt lgkmcnt(15)
	ds_write_b32 v182, v113 offset:4352
	s_waitcnt lgkmcnt(15)
	ds_write_b32 v182, v114 offset:4608
	s_waitcnt lgkmcnt(15)
	ds_write_b32 v182, v115 offset:4864
	s_waitcnt lgkmcnt(15)
	ds_write_b32 v182, v116 offset:5120
	s_waitcnt lgkmcnt(15)
	ds_write_b32 v182, v117 offset:5376
	s_waitcnt lgkmcnt(15)
	ds_write_b32 v182, v118 offset:5632
	s_waitcnt lgkmcnt(15)
	ds_write_b32 v182, v119 offset:5888
	s_waitcnt lgkmcnt(15)
	ds_write_b32 v182, v120 offset:6144
	s_waitcnt lgkmcnt(15)
	ds_write_b32 v182, v121 offset:6400
	s_waitcnt lgkmcnt(15)
	ds_write_b32 v182, v122 offset:6656
	ds_read_b32 v178, v156 offset:4988
	v_add_u32_e32 v180, 148, v180
	v_mov_b32_e32 v181, 0x7f800000
	s_waitcnt lgkmcnt(0)
